# sa2 + packed SwiGLU epilogue + accumulator zeroing with v_mov_b64 in five GEMM unit headers
# speedup vs baseline: 1.0150x; 1.0048x over previous
.LBB0_246:
	s_ashr_i32 s19, s18, 31
	s_lshl_b64 s[26:27], s[18:19], 19
	s_add_u32 s26, s54, s26
	s_addc_u32 s27, s55, s27
	s_and_b64 s[28:29], s[4:5], exec
	s_cselect_b32 s19, s27, s35
	s_cselect_b32 s85, s26, s34
	s_ashr_i32 s17, s16, 31
	s_lshl_b64 s[28:29], s[16:17], 19
	s_add_u32 s28, s21, s28
	s_addc_u32 s29, s25, s29
	s_and_b64 s[58:59], s[4:5], exec
	s_cselect_b32 s17, s29, s53
	s_cselect_b32 s88, s28, s52
	s_cmp_lg_u32 s36, 0
	s_cselect_b64 s[36:37], -1, 0
	s_add_u32 s91, s52, 0x100
	v_mov_b64_e32 v[0:1], 0
	v_lshl_add_u64 v[146:147], s[34:35], 0, v[138:139]
	v_lshl_add_u64 v[148:149], s[34:35], 0, v[140:141]
	s_addc_u32 s92, s53, 0
	s_mov_b32 s93, -2
	s_mov_b64 s[52:53], 0
	v_mov_b64_e32 v[2:3], 0
	v_mov_b64_e32 v[4:5], 0
	v_mov_b64_e32 v[6:7], 0
	v_mov_b64_e32 v[16:17], 0
	v_mov_b64_e32 v[18:19], 0
	v_mov_b64_e32 v[20:21], 0
	v_mov_b64_e32 v[22:23], 0
	v_mov_b64_e32 v[32:33], 0
	v_mov_b64_e32 v[34:35], 0
	v_mov_b64_e32 v[36:37], 0
	v_mov_b64_e32 v[38:39], 0
	v_mov_b64_e32 v[48:49], 0
	v_mov_b64_e32 v[50:51], 0
	v_mov_b64_e32 v[52:53], 0
	v_mov_b64_e32 v[54:55], 0
	v_mov_b64_e32 v[8:9], 0
	v_mov_b64_e32 v[10:11], 0
	v_mov_b64_e32 v[12:13], 0
	v_mov_b64_e32 v[14:15], 0
	v_mov_b64_e32 v[24:25], 0
	v_mov_b64_e32 v[26:27], 0
	v_mov_b64_e32 v[28:29], 0
	v_mov_b64_e32 v[30:31], 0
	v_mov_b64_e32 v[40:41], 0
	v_mov_b64_e32 v[42:43], 0
	v_mov_b64_e32 v[44:45], 0
	v_mov_b64_e32 v[46:47], 0
	v_mov_b64_e32 v[56:57], 0
	v_mov_b64_e32 v[58:59], 0
	v_mov_b64_e32 v[60:61], 0
	v_mov_b64_e32 v[62:63], 0
	v_mov_b64_e32 v[64:65], 0
	v_mov_b64_e32 v[66:67], 0
	v_mov_b64_e32 v[68:69], 0
	v_mov_b64_e32 v[70:71], 0
	v_mov_b64_e32 v[80:81], 0
	v_mov_b64_e32 v[82:83], 0
	v_mov_b64_e32 v[84:85], 0
	v_mov_b64_e32 v[86:87], 0
	v_mov_b64_e32 v[96:97], 0
	v_mov_b64_e32 v[98:99], 0
	v_mov_b64_e32 v[100:101], 0
	v_mov_b64_e32 v[102:103], 0
	v_mov_b64_e32 v[112:113], 0
	v_mov_b64_e32 v[114:115], 0
	v_mov_b64_e32 v[116:117], 0
	v_mov_b64_e32 v[118:119], 0
	v_mov_b64_e32 v[72:73], 0
	v_mov_b64_e32 v[74:75], 0
	v_mov_b64_e32 v[76:77], 0
	v_mov_b64_e32 v[78:79], 0
	v_mov_b64_e32 v[88:89], 0
	v_mov_b64_e32 v[90:91], 0
	v_mov_b64_e32 v[92:93], 0
	v_mov_b64_e32 v[94:95], 0
	v_mov_b64_e32 v[104:105], 0
	v_mov_b64_e32 v[106:107], 0
	v_mov_b64_e32 v[108:109], 0
	v_mov_b64_e32 v[110:111], 0
	v_mov_b64_e32 v[120:121], 0
	v_mov_b64_e32 v[122:123], 0
	v_mov_b64_e32 v[124:125], 0
	v_mov_b64_e32 v[126:127], 0

.LBB0_323:
	s_add_u32 s78, s28, 0x100
	v_mov_b64_e32 v[0:1], 0
	s_addc_u32 s79, s29, 0
	s_mov_b32 s80, -2
	v_mov_b64_e32 v[2:3], 0
	v_mov_b64_e32 v[4:5], 0
	v_mov_b64_e32 v[6:7], 0
	v_mov_b64_e32 v[8:9], 0
	v_mov_b64_e32 v[10:11], 0
	v_mov_b64_e32 v[20:21], 0
	v_mov_b64_e32 v[22:23], 0
	v_mov_b64_e32 v[24:25], 0
	v_mov_b64_e32 v[26:27], 0
	v_mov_b64_e32 v[36:37], 0
	v_mov_b64_e32 v[38:39], 0
	v_mov_b64_e32 v[40:41], 0
	v_mov_b64_e32 v[42:43], 0
	v_mov_b64_e32 v[52:53], 0
	v_mov_b64_e32 v[54:55], 0
	v_mov_b64_e32 v[12:13], 0
	v_mov_b64_e32 v[14:15], 0
	v_mov_b64_e32 v[16:17], 0
	v_mov_b64_e32 v[18:19], 0
	v_mov_b64_e32 v[28:29], 0
	v_mov_b64_e32 v[30:31], 0
	v_mov_b64_e32 v[32:33], 0
	v_mov_b64_e32 v[34:35], 0
	v_mov_b64_e32 v[44:45], 0
	v_mov_b64_e32 v[46:47], 0
	v_mov_b64_e32 v[48:49], 0
	v_mov_b64_e32 v[50:51], 0
	v_mov_b64_e32 v[56:57], 0
	v_mov_b64_e32 v[58:59], 0
	v_mov_b64_e32 v[60:61], 0
	v_mov_b64_e32 v[62:63], 0
	v_mov_b64_e32 v[64:65], 0
	v_mov_b64_e32 v[66:67], 0
	v_mov_b64_e32 v[68:69], 0
	v_mov_b64_e32 v[70:71], 0
	v_mov_b64_e32 v[72:73], 0
	v_mov_b64_e32 v[74:75], 0
	v_mov_b64_e32 v[84:85], 0
	v_mov_b64_e32 v[86:87], 0
	v_mov_b64_e32 v[88:89], 0
	v_mov_b64_e32 v[90:91], 0
	v_mov_b64_e32 v[100:101], 0
	v_mov_b64_e32 v[102:103], 0
	v_mov_b64_e32 v[104:105], 0
	v_mov_b64_e32 v[106:107], 0
	v_mov_b64_e32 v[116:117], 0
	v_mov_b64_e32 v[118:119], 0
	v_mov_b64_e32 v[76:77], 0
	v_mov_b64_e32 v[78:79], 0
	v_mov_b64_e32 v[80:81], 0
	v_mov_b64_e32 v[82:83], 0
	v_mov_b64_e32 v[92:93], 0
	v_mov_b64_e32 v[94:95], 0
	v_mov_b64_e32 v[96:97], 0
	v_mov_b64_e32 v[98:99], 0
	v_mov_b64_e32 v[108:109], 0
	v_mov_b64_e32 v[110:111], 0
	v_mov_b64_e32 v[112:113], 0
	v_mov_b64_e32 v[114:115], 0
	v_mov_b64_e32 v[120:121], 0
	v_mov_b64_e32 v[122:123], 0
	v_mov_b64_e32 v[124:125], 0
	v_mov_b64_e32 v[126:127], 0

.LBB0_490:
	s_ashr_i32 s21, s20, 31
	s_lshl_b64 s[22:23], s[20:21], 19
	s_add_u32 s22, s54, s22
	s_addc_u32 s23, s55, s23
	s_and_b64 s[24:25], s[4:5], exec
	s_cselect_b32 s1, s23, s27
	s_cselect_b32 s7, s22, s26
	s_ashr_i32 s19, s18, 31
	s_lshl_b64 s[24:25], s[18:19], 19
	s_add_u32 s24, s34, s24
	s_addc_u32 s25, s35, s25
	s_and_b64 s[30:31], s[4:5], exec
	s_cselect_b32 s8, s25, s29
	s_cselect_b32 s17, s24, s28
	s_add_u32 s26, s26, 0x40080
	s_addc_u32 s27, s27, 0
	s_add_u32 s19, s28, 0x100
	v_mov_b64_e32 v[0:1], 0
	s_addc_u32 s21, s29, 0
	s_mov_b32 s68, -2
	v_mov_b64_e32 v[2:3], 0
	v_mov_b64_e32 v[4:5], 0
	v_mov_b64_e32 v[6:7], 0
	v_mov_b64_e32 v[16:17], 0
	v_mov_b64_e32 v[18:19], 0
	v_mov_b64_e32 v[20:21], 0
	v_mov_b64_e32 v[22:23], 0
	v_mov_b64_e32 v[32:33], 0
	v_mov_b64_e32 v[34:35], 0
	v_mov_b64_e32 v[36:37], 0
	v_mov_b64_e32 v[38:39], 0
	v_mov_b64_e32 v[48:49], 0
	v_mov_b64_e32 v[50:51], 0
	v_mov_b64_e32 v[52:53], 0
	v_mov_b64_e32 v[54:55], 0
	v_mov_b64_e32 v[8:9], 0
	v_mov_b64_e32 v[10:11], 0
	v_mov_b64_e32 v[12:13], 0
	v_mov_b64_e32 v[14:15], 0
	v_mov_b64_e32 v[24:25], 0
	v_mov_b64_e32 v[26:27], 0
	v_mov_b64_e32 v[28:29], 0
	v_mov_b64_e32 v[30:31], 0
	v_mov_b64_e32 v[40:41], 0
	v_mov_b64_e32 v[42:43], 0
	v_mov_b64_e32 v[44:45], 0
	v_mov_b64_e32 v[46:47], 0
	v_mov_b64_e32 v[56:57], 0
	v_mov_b64_e32 v[58:59], 0
	v_mov_b64_e32 v[60:61], 0
	v_mov_b64_e32 v[62:63], 0
	v_mov_b64_e32 v[64:65], 0
	v_mov_b64_e32 v[66:67], 0
	v_mov_b64_e32 v[68:69], 0
	v_mov_b64_e32 v[70:71], 0
	v_mov_b64_e32 v[80:81], 0
	v_mov_b64_e32 v[82:83], 0
	v_mov_b64_e32 v[84:85], 0
	v_mov_b64_e32 v[86:87], 0
	v_mov_b64_e32 v[96:97], 0
	v_mov_b64_e32 v[98:99], 0
	v_mov_b64_e32 v[100:101], 0
	v_mov_b64_e32 v[102:103], 0
	v_mov_b64_e32 v[112:113], 0
	v_mov_b64_e32 v[114:115], 0
	v_mov_b64_e32 v[116:117], 0
	v_mov_b64_e32 v[118:119], 0
	v_mov_b64_e32 v[72:73], 0
	v_mov_b64_e32 v[74:75], 0
	v_mov_b64_e32 v[76:77], 0
	v_mov_b64_e32 v[78:79], 0
	v_mov_b64_e32 v[88:89], 0
	v_mov_b64_e32 v[90:91], 0
	v_mov_b64_e32 v[92:93], 0
	v_mov_b64_e32 v[94:95], 0
	v_mov_b64_e32 v[104:105], 0
	v_mov_b64_e32 v[106:107], 0
	v_mov_b64_e32 v[108:109], 0
	v_mov_b64_e32 v[110:111], 0
	v_mov_b64_e32 v[120:121], 0
	v_mov_b64_e32 v[122:123], 0
	v_mov_b64_e32 v[124:125], 0
	v_mov_b64_e32 v[126:127], 0

.LBB0_1046:
	s_ashr_i32 s19, s18, 31
	s_lshl_b64 s[20:21], s[18:19], 19
	s_add_u32 s20, s10, s20
	s_addc_u32 s21, s11, s21
	s_and_b64 s[22:23], s[4:5], exec
	s_cselect_b32 s19, s21, s27
	s_cselect_b32 s70, s20, s26
	s_ashr_i32 s17, s16, 31
	s_lshl_b64 s[22:23], s[16:17], 19
	s_add_u32 s22, s42, s22
	s_addc_u32 s23, s43, s23
	s_and_b64 s[34:35], s[4:5], exec
	s_cselect_b32 s17, s23, s31
	s_cselect_b32 s71, s22, s30
	s_cmp_lg_u32 s28, 0
	s_cselect_b64 s[28:29], -1, 0
	s_add_u32 s72, s30, 0x100
	v_mov_b64_e32 v[0:1], 0
	v_lshl_add_u64 v[146:147], s[26:27], 0, v[138:139]
	v_lshl_add_u64 v[148:149], s[26:27], 0, v[140:141]
	s_addc_u32 s73, s31, 0
	s_mov_b32 s74, -2
	s_mov_b64 s[30:31], 0
	v_mov_b64_e32 v[2:3], 0
	v_mov_b64_e32 v[4:5], 0
	v_mov_b64_e32 v[6:7], 0
	v_mov_b64_e32 v[16:17], 0
	v_mov_b64_e32 v[18:19], 0
	v_mov_b64_e32 v[20:21], 0
	v_mov_b64_e32 v[22:23], 0
	v_mov_b64_e32 v[32:33], 0
	v_mov_b64_e32 v[34:35], 0
	v_mov_b64_e32 v[36:37], 0
	v_mov_b64_e32 v[38:39], 0
	v_mov_b64_e32 v[48:49], 0
	v_mov_b64_e32 v[50:51], 0
	v_mov_b64_e32 v[52:53], 0
	v_mov_b64_e32 v[54:55], 0
	v_mov_b64_e32 v[8:9], 0
	v_mov_b64_e32 v[10:11], 0
	v_mov_b64_e32 v[12:13], 0
	v_mov_b64_e32 v[14:15], 0
	v_mov_b64_e32 v[24:25], 0
	v_mov_b64_e32 v[26:27], 0
	v_mov_b64_e32 v[28:29], 0
	v_mov_b64_e32 v[30:31], 0
	v_mov_b64_e32 v[40:41], 0
	v_mov_b64_e32 v[42:43], 0
	v_mov_b64_e32 v[44:45], 0
	v_mov_b64_e32 v[46:47], 0
	v_mov_b64_e32 v[56:57], 0
	v_mov_b64_e32 v[58:59], 0
	v_mov_b64_e32 v[60:61], 0
	v_mov_b64_e32 v[62:63], 0
	v_mov_b64_e32 v[64:65], 0
	v_mov_b64_e32 v[66:67], 0
	v_mov_b64_e32 v[68:69], 0
	v_mov_b64_e32 v[70:71], 0
	v_mov_b64_e32 v[80:81], 0
	v_mov_b64_e32 v[82:83], 0
	v_mov_b64_e32 v[84:85], 0
	v_mov_b64_e32 v[86:87], 0
	v_mov_b64_e32 v[96:97], 0
	v_mov_b64_e32 v[98:99], 0
	v_mov_b64_e32 v[100:101], 0
	v_mov_b64_e32 v[102:103], 0
	v_mov_b64_e32 v[112:113], 0
	v_mov_b64_e32 v[114:115], 0
	v_mov_b64_e32 v[116:117], 0
	v_mov_b64_e32 v[118:119], 0
	v_mov_b64_e32 v[72:73], 0
	v_mov_b64_e32 v[74:75], 0
	v_mov_b64_e32 v[76:77], 0
	v_mov_b64_e32 v[78:79], 0
	v_mov_b64_e32 v[88:89], 0
	v_mov_b64_e32 v[90:91], 0
	v_mov_b64_e32 v[92:93], 0
	v_mov_b64_e32 v[94:95], 0
	v_mov_b64_e32 v[104:105], 0
	v_mov_b64_e32 v[106:107], 0
	v_mov_b64_e32 v[108:109], 0
	v_mov_b64_e32 v[110:111], 0
	v_mov_b64_e32 v[120:121], 0
	v_mov_b64_e32 v[122:123], 0
	v_mov_b64_e32 v[124:125], 0
	v_mov_b64_e32 v[126:127], 0

.LBB0_1123:
	s_add_u32 s50, s20, 0x100
	v_mov_b64_e32 v[0:1], 0
	s_addc_u32 s51, s21, 0
	s_mov_b32 s52, -2
	v_mov_b64_e32 v[2:3], 0
	v_mov_b64_e32 v[4:5], 0
	v_mov_b64_e32 v[6:7], 0
	v_mov_b64_e32 v[8:9], 0
	v_mov_b64_e32 v[10:11], 0
	v_mov_b64_e32 v[20:21], 0
	v_mov_b64_e32 v[22:23], 0
	v_mov_b64_e32 v[24:25], 0
	v_mov_b64_e32 v[26:27], 0
	v_mov_b64_e32 v[36:37], 0
	v_mov_b64_e32 v[38:39], 0
	v_mov_b64_e32 v[40:41], 0
	v_mov_b64_e32 v[42:43], 0
	v_mov_b64_e32 v[52:53], 0
	v_mov_b64_e32 v[54:55], 0
	v_mov_b64_e32 v[12:13], 0
	v_mov_b64_e32 v[14:15], 0
	v_mov_b64_e32 v[16:17], 0
	v_mov_b64_e32 v[18:19], 0
	v_mov_b64_e32 v[28:29], 0
	v_mov_b64_e32 v[30:31], 0
	v_mov_b64_e32 v[32:33], 0
	v_mov_b64_e32 v[34:35], 0
	v_mov_b64_e32 v[44:45], 0
	v_mov_b64_e32 v[46:47], 0
	v_mov_b64_e32 v[48:49], 0
	v_mov_b64_e32 v[50:51], 0
	v_mov_b64_e32 v[56:57], 0
	v_mov_b64_e32 v[58:59], 0
	v_mov_b64_e32 v[60:61], 0
	v_mov_b64_e32 v[62:63], 0
	v_mov_b64_e32 v[64:65], 0
	v_mov_b64_e32 v[66:67], 0
	v_mov_b64_e32 v[68:69], 0
	v_mov_b64_e32 v[70:71], 0
	v_mov_b64_e32 v[72:73], 0
	v_mov_b64_e32 v[74:75], 0
	v_mov_b64_e32 v[84:85], 0
	v_mov_b64_e32 v[86:87], 0
	v_mov_b64_e32 v[88:89], 0
	v_mov_b64_e32 v[90:91], 0
	v_mov_b64_e32 v[100:101], 0
	v_mov_b64_e32 v[102:103], 0
	v_mov_b64_e32 v[104:105], 0
	v_mov_b64_e32 v[106:107], 0
	v_mov_b64_e32 v[116:117], 0
	v_mov_b64_e32 v[118:119], 0
	v_mov_b64_e32 v[76:77], 0
	v_mov_b64_e32 v[78:79], 0
	v_mov_b64_e32 v[80:81], 0
	v_mov_b64_e32 v[82:83], 0
	v_mov_b64_e32 v[92:93], 0
	v_mov_b64_e32 v[94:95], 0
	v_mov_b64_e32 v[96:97], 0
	v_mov_b64_e32 v[98:99], 0
	v_mov_b64_e32 v[108:109], 0
	v_mov_b64_e32 v[110:111], 0
	v_mov_b64_e32 v[112:113], 0
	v_mov_b64_e32 v[114:115], 0
	v_mov_b64_e32 v[120:121], 0
	v_mov_b64_e32 v[122:123], 0
	v_mov_b64_e32 v[124:125], 0
	v_mov_b64_e32 v[126:127], 0
